# combined: static waves 4-7 priority raise + D3 hand-off write without execz branch + counted vmcnt(8) at the G1 K-loop header
# speedup vs baseline: 1.0054x; 1.0047x over previous
; #define PG8_STAGE(bufoff, gbase, voff) do { _Pragma("unroll") for (int _i = 0; _i < 2; ++_i) \
;         __builtin_amdgcn_global_load_lds((const unsigned*)((const char*)(gbase) + (voff)[_i]), (PG8_LAS unsigned*)(lds + (bufoff) + ldsw + _i * 8192), 16, 0, 0); } while (0)
; #define PG8_LDA(dst, b, h) do { _Pragma("unroll") for (int m = 0; m < 4; ++m) _Pragma("unroll") for (int k = 0; k < 2; ++k) dst[m][k] = *(const PG8_LAS bf16x8*)(lds + PG8_SA(b, h) + aoff + m * 2048 + k * 1024); } while (0)
; #define PG8_LDB(dst, b, h) do { _Pragma("unroll") for (int n = 0; n < 2; ++n) _Pragma("unroll") for (int k = 0; k < 2; ++k) dst[n][k] = *(const PG8_LAS bf16x8*)(lds + PG8_SB(b, h) + boff + n * 2048 + k * 1024); } while (0)
; #define PG8_MMA(ai, bj, At, Bt) do { __builtin_amdgcn_s_setprio(1); _Pragma("unroll") for (int m = 0; m < 4; ++m) _Pragma("unroll") for (int n = 0; n < 2; ++n) _Pragma("unroll") for (int k = 0; k < 2; ++k) \
;         acc[ai][bj][m][n] = __builtin_amdgcn_mfma_f32_16x16x32_bf16(Bt[n][k], At[m][k], acc[ai][bj][m][n], 0, 0, 0); __builtin_amdgcn_s_setprio(0); } while (0)
; #define PG8_WAIT_V(n) asm volatile("s_waitcnt vmcnt(" #n ")" ::: "memory")
; #define PG8_WAIT_L(n) asm volatile("s_waitcnt lgkmcnt(" #n ")" ::: "memory")
; #define PG8_BAR __builtin_amdgcn_s_barrier()
; template <class Epi, class Sched, bool ALIGN_EPI = false, bool SP2 = false>
; __device__ __forceinline__ void gemm_phase(PG8_LAS unsigned char* lds, const Gemm g, const Sched& S, const Epi& E, const int tid_in) {
;     ...
;         for (int t = 0; t < nt; t += 2) {
;             const bool last = (t == nt - 2);
;             const char* a1 = cA + (size_t)(t + 1) * kstep;
;             const char* a2 = last ? nA : cA + (size_t)(t + 2) * kstep; const char* b2 = last ? nB : cB + (size_t)(t + 2) * kstep;
;             const char* a3 = a2 + kstep; const char* b3 = b2 + kstep;
;             if (last && has_next) S.a_ready(nxt);
;             if constexpr (SP2) {
;             PG8_LDB(B0, 0, 0); PG8_LDB(B1, 0, 1); PG8_SCHED; PG8_LDA(At, 0, 0); PG8_STAGE(PG8_SA(1, 1), a1 + hstep, voffA);
;             PG8_WAIT_V(8); PG8_WAIT_L(0); PG8_BAR; PG8_MMA(0, 0, At, B0); PG8_MMA(0, 1, At, B1); PG8_BAR; PG8_SCHED;
;             PG8_LDA(At, 0, 1); PG8_STAGE(PG8_SB(0, 0), b2, voffB); PG8_STAGE(PG8_SB(0, 1), b2 + hstep, voffB); PG8_STAGE(PG8_SA(0, 0), a2, voffA);
.Lprio_done_593:
.LBB0_593:
	s_add_u32 s8, s42, 0xfff80080
	s_addc_u32 s9, s43, -1
	s_add_i32 s61, 0, 0x10000
	s_cmp_eq_u32 s57, 28
	s_cselect_b32 s11, s12, s9
	s_cselect_b32 s10, s13, s8
	s_cselect_b32 s9, s41, s55
	s_cselect_b32 s8, s44, s45
	s_add_i32 s64, 0, 0x14000
	s_waitcnt vmcnt(8)
	v_add_u32_e32 v92, s61, v196
	v_add_u32_e32 v96, s64, v196
	ds_read_b128 v[64:67], v92
	ds_read_b128 v[68:71], v92 offset:1024
	ds_read_b128 v[88:91], v92 offset:2048
	ds_read_b128 v[92:95], v92 offset:3072
	ds_read_b128 v[106:109], v96
	ds_read_b128 v[110:113], v96 offset:1024
	ds_read_b128 v[130:133], v96 offset:2048
	ds_read_b128 v[134:137], v96 offset:3072
	v_lshl_add_u64 v[180:181], s[42:43], 0, v[172:173]
	s_add_i32 m0, s20, 0xc000
	ds_read_b128 v[176:179], v198
	ds_read_b128 v[200:203], v198 offset:1024
	ds_read_b128 v[204:207], v198 offset:2048
	ds_read_b128 v[208:211], v198 offset:3072
	ds_read_b128 v[212:215], v198 offset:4096
	ds_read_b128 v[216:219], v198 offset:5120
	ds_read_b128 v[220:223], v198 offset:6144
	ds_read_b128 v[242:245], v198 offset:7168
	global_load_lds_dwordx4 v[180:181], off
	v_lshl_add_u64 v[180:181], s[42:43], 0, v[174:175]
	s_add_i32 m0, s20, 0xe000
	s_nop 0
	global_load_lds_dwordx4 v[180:181], off
	s_waitcnt vmcnt(8)
	s_waitcnt lgkmcnt(0)
	s_barrier
	s_waitcnt lgkmcnt(0)
	v_mfma_f32_16x16x32_bf16 v[158:161], v[64:67], v[176:179], v[158:161]
	v_mfma_f32_16x16x32_bf16 v[154:157], v[88:91], v[176:179], v[154:157]
	v_mfma_f32_16x16x32_bf16 v[142:145], v[64:67], v[204:207], v[142:145]
	v_mfma_f32_16x16x32_bf16 v[138:141], v[88:91], v[204:207], v[138:141]
	v_mfma_f32_16x16x32_bf16 v[118:121], v[64:67], v[212:215], v[118:121]
	v_mfma_f32_16x16x32_bf16 v[114:117], v[88:91], v[212:215], v[114:117]
	v_mfma_f32_16x16x32_bf16 v[84:87], v[64:67], v[220:223], v[84:87]
	v_mfma_f32_16x16x32_bf16 v[80:83], v[88:91], v[220:223], v[80:83]
	v_mfma_f32_16x16x32_bf16 v[158:161], v[68:71], v[200:203], v[158:161]
	v_mfma_f32_16x16x32_bf16 v[154:157], v[92:95], v[200:203], v[154:157]
	v_mfma_f32_16x16x32_bf16 v[142:145], v[68:71], v[208:211], v[142:145]
	v_mfma_f32_16x16x32_bf16 v[138:141], v[92:95], v[208:211], v[138:141]
	v_mfma_f32_16x16x32_bf16 v[118:121], v[68:71], v[216:219], v[118:121]
	v_mfma_f32_16x16x32_bf16 v[114:117], v[92:95], v[216:219], v[114:117]
	v_mfma_f32_16x16x32_bf16 v[84:87], v[68:71], v[242:245], v[84:87]
	v_mfma_f32_16x16x32_bf16 v[80:83], v[92:95], v[242:245], v[80:83]
	v_mfma_f32_16x16x32_bf16 v[150:153], v[106:109], v[176:179], v[150:153]
	v_mfma_f32_16x16x32_bf16 v[146:149], v[130:133], v[176:179], v[146:149]
	v_mfma_f32_16x16x32_bf16 v[126:129], v[106:109], v[204:207], v[126:129]
	v_mfma_f32_16x16x32_bf16 v[122:125], v[130:133], v[204:207], v[122:125]
	v_mfma_f32_16x16x32_bf16 v[102:105], v[106:109], v[212:215], v[102:105]
	v_mfma_f32_16x16x32_bf16 v[98:101], v[130:133], v[212:215], v[98:101]
	v_mfma_f32_16x16x32_bf16 v[76:79], v[106:109], v[220:223], v[76:79]
	v_mfma_f32_16x16x32_bf16 v[72:75], v[130:133], v[220:223], v[72:75]
	v_mfma_f32_16x16x32_bf16 v[150:153], v[110:113], v[200:203], v[150:153]
	v_mfma_f32_16x16x32_bf16 v[146:149], v[134:137], v[200:203], v[146:149]
	v_mfma_f32_16x16x32_bf16 v[126:129], v[110:113], v[208:211], v[126:129]
	v_mfma_f32_16x16x32_bf16 v[122:125], v[134:137], v[208:211], v[122:125]
	v_mfma_f32_16x16x32_bf16 v[102:105], v[110:113], v[216:219], v[102:105]
	v_mfma_f32_16x16x32_bf16 v[98:101], v[134:137], v[216:219], v[98:101]
	v_mfma_f32_16x16x32_bf16 v[76:79], v[110:113], v[242:245], v[76:79]
	v_mfma_f32_16x16x32_bf16 v[72:75], v[134:137], v[242:245], v[72:75]
	s_barrier
	s_add_i32 s61, s61, s19
	v_lshl_add_u64 v[180:181], s[8:9], 0, v[164:165]
	s_mov_b32 m0, s61
	ds_read_b128 v[176:179], v198 offset:16384
	ds_read_b128 v[200:203], v198 offset:17408
	ds_read_b128 v[204:207], v198 offset:18432
	ds_read_b128 v[208:211], v198 offset:19456
	ds_read_b128 v[212:215], v198 offset:20480
	ds_read_b128 v[216:219], v198 offset:21504
	ds_read_b128 v[220:223], v198 offset:22528
	ds_read_b128 v[242:245], v198 offset:23552
	global_load_lds_dwordx4 v[180:181], off
	s_add_i32 m0, s61, 0x2000
	s_add_u32 s62, s8, 0x80000
	v_lshl_add_u64 v[184:185], s[8:9], 0, v[168:169]
	s_addc_u32 s63, s9, 0
	s_add_i32 s61, s64, s19
	global_load_lds_dwordx4 v[184:185], off
	v_lshl_add_u64 v[186:187], s[62:63], 0, v[164:165]
	s_mov_b32 m0, s61
	v_lshl_add_u64 v[224:225], s[10:11], 0, v[166:167]
	global_load_lds_dwordx4 v[186:187], off
	v_lshl_add_u64 v[186:187], s[62:63], 0, v[168:169]
	s_add_i32 m0, s61, 0x2000
	s_nop 0
	global_load_lds_dwordx4 v[186:187], off
	v_lshl_add_u64 v[186:187], s[10:11], 0, v[162:163]
	s_mov_b32 m0, s20
	s_nop 0
	global_load_lds_dwordx4 v[186:187], off
	s_mov_b32 m0, s22
	s_nop 0
	global_load_lds_dwordx4 v[224:225], off
	s_waitcnt vmcnt(8)
	s_waitcnt lgkmcnt(0)
	s_barrier
; #define PG8_STAGE(bufoff, gbase, voff) do { _Pragma("unroll") for (int _i = 0; _i < 2; ++_i) \
;         __builtin_amdgcn_global_load_lds((const unsigned*)((const char*)(gbase) + (voff)[_i]), (PG8_LAS unsigned*)(lds + (bufoff) + ldsw + _i * 8192), 16, 0, 0); } while (0)
; #define PG8_LDA(dst, b, h) do { _Pragma("unroll") for (int m = 0; m < 4; ++m) _Pragma("unroll") for (int k = 0; k < 2; ++k) dst[m][k] = *(const PG8_LAS bf16x8*)(lds + PG8_SA(b, h) + aoff + m * 2048 + k * 1024); } while (0)
; #define PG8_LDB(dst, b, h) do { _Pragma("unroll") for (int n = 0; n < 2; ++n) _Pragma("unroll") for (int k = 0; k < 2; ++k) dst[n][k] = *(const PG8_LAS bf16x8*)(lds + PG8_SB(b, h) + boff + n * 2048 + k * 1024); } while (0)
; #define PG8_MMA(ai, bj, At, Bt) do { __builtin_amdgcn_s_setprio(1); _Pragma("unroll") for (int m = 0; m < 4; ++m) _Pragma("unroll") for (int n = 0; n < 2; ++n) _Pragma("unroll") for (int k = 0; k < 2; ++k) \
;         acc[ai][bj][m][n] = __builtin_amdgcn_mfma_f32_16x16x32_bf16(Bt[n][k], At[m][k], acc[ai][bj][m][n], 0, 0, 0); __builtin_amdgcn_s_setprio(0); } while (0)
; #define PG8_WAIT_V(n) asm volatile("s_waitcnt vmcnt(" #n ")" ::: "memory")
; #define PG8_WAIT_L(n) asm volatile("s_waitcnt lgkmcnt(" #n ")" ::: "memory")
; #define PG8_BAR __builtin_amdgcn_s_barrier()
; #define PG8_SCHED __builtin_amdgcn_sched_barrier(0)
; template <class Epi, class Sched, bool ALIGN_EPI = false, bool SP2 = false>
; __device__ __forceinline__ void gemm_phase(PG8_LAS unsigned char* lds, const Gemm g, const Sched& S, const Epi& E, const int tid_in) {
;     ...
;             PG8_WAIT_V(8); PG8_WAIT_L(0); PG8_BAR; PG8_MMA(1, 0, At, B0); PG8_MMA(1, 1, At, B1); PG8_BAR; PG8_SCHED;
;             PG8_LDB(B0, 1, 0); PG8_LDB(B1, 1, 1); PG8_SCHED; PG8_LDA(At, 1, 0); PG8_STAGE(PG8_SA(0, 1), a2 + hstep, voffA);
;             PG8_WAIT_V(8); PG8_WAIT_L(0); PG8_BAR; PG8_MMA(0, 0, At, B0); PG8_MMA(0, 1, At, B1); PG8_BAR; PG8_SCHED;
	s_waitcnt lgkmcnt(0)
	v_mfma_f32_16x16x32_bf16 v[60:63], v[64:67], v[176:179], v[60:63]
	v_mfma_f32_16x16x32_bf16 v[56:59], v[88:91], v[176:179], v[56:59]
	v_mfma_f32_16x16x32_bf16 v[44:47], v[64:67], v[204:207], v[44:47]
	v_mfma_f32_16x16x32_bf16 v[40:43], v[88:91], v[204:207], v[40:43]
	v_mfma_f32_16x16x32_bf16 v[28:31], v[64:67], v[212:215], v[28:31]
	v_mfma_f32_16x16x32_bf16 v[24:27], v[88:91], v[212:215], v[24:27]
	v_mfma_f32_16x16x32_bf16 v[12:15], v[64:67], v[220:223], v[12:15]
	v_mfma_f32_16x16x32_bf16 v[8:11], v[88:91], v[220:223], v[8:11]
	v_mfma_f32_16x16x32_bf16 v[60:63], v[68:71], v[200:203], v[60:63]
	v_mfma_f32_16x16x32_bf16 v[56:59], v[92:95], v[200:203], v[56:59]
	v_mfma_f32_16x16x32_bf16 v[44:47], v[68:71], v[208:211], v[44:47]
	v_mfma_f32_16x16x32_bf16 v[40:43], v[92:95], v[208:211], v[40:43]
	v_mfma_f32_16x16x32_bf16 v[28:31], v[68:71], v[216:219], v[28:31]
	v_mfma_f32_16x16x32_bf16 v[24:27], v[92:95], v[216:219], v[24:27]
	v_mfma_f32_16x16x32_bf16 v[12:15], v[68:71], v[242:245], v[12:15]
	v_mfma_f32_16x16x32_bf16 v[8:11], v[92:95], v[242:245], v[8:11]
	v_mfma_f32_16x16x32_bf16 v[52:55], v[106:109], v[176:179], v[52:55]
	v_mfma_f32_16x16x32_bf16 v[48:51], v[130:133], v[176:179], v[48:51]
	v_mfma_f32_16x16x32_bf16 v[36:39], v[106:109], v[204:207], v[36:39]
	v_mfma_f32_16x16x32_bf16 v[32:35], v[130:133], v[204:207], v[32:35]
	v_mfma_f32_16x16x32_bf16 v[20:23], v[106:109], v[212:215], v[20:23]
	v_mfma_f32_16x16x32_bf16 v[16:19], v[130:133], v[212:215], v[16:19]
	v_mfma_f32_16x16x32_bf16 v[4:7], v[106:109], v[220:223], v[4:7]
	v_mfma_f32_16x16x32_bf16 v[0:3], v[130:133], v[220:223], v[0:3]
	v_mfma_f32_16x16x32_bf16 v[52:55], v[110:113], v[200:203], v[52:55]
	v_mfma_f32_16x16x32_bf16 v[48:51], v[134:137], v[200:203], v[48:51]
	v_mfma_f32_16x16x32_bf16 v[36:39], v[110:113], v[208:211], v[36:39]
	v_mfma_f32_16x16x32_bf16 v[32:35], v[134:137], v[208:211], v[32:35]
	v_mfma_f32_16x16x32_bf16 v[20:23], v[110:113], v[216:219], v[20:23]
	v_mfma_f32_16x16x32_bf16 v[16:19], v[134:137], v[216:219], v[16:19]
	v_mfma_f32_16x16x32_bf16 v[4:7], v[110:113], v[242:245], v[4:7]
	v_mfma_f32_16x16x32_bf16 v[0:3], v[134:137], v[242:245], v[0:3]
	s_barrier
	s_add_i32 s61, 0, 0x18000
	s_add_i32 s62, 0, 0x1c000
	v_add_u32_e32 v92, s61, v196
	v_add_u32_e32 v96, s62, v196
	ds_read_b128 v[64:67], v92
	ds_read_b128 v[68:71], v92 offset:1024
	ds_read_b128 v[88:91], v92 offset:2048
	ds_read_b128 v[92:95], v92 offset:3072
	ds_read_b128 v[106:109], v96
	ds_read_b128 v[110:113], v96 offset:1024
	ds_read_b128 v[130:133], v96 offset:2048
	ds_read_b128 v[134:137], v96 offset:3072
	s_add_u32 s10, s10, 0x80000
	s_addc_u32 s11, s11, 0
	s_mov_b32 m0, s23
	v_lshl_add_u64 v[250:251], s[10:11], 0, v[162:163]
	ds_read_b128 v[176:179], v198 offset:32768
	ds_read_b128 v[200:203], v198 offset:33792
	ds_read_b128 v[204:207], v198 offset:34816
	ds_read_b128 v[208:211], v198 offset:35840
	ds_read_b128 v[212:215], v198 offset:36864
	ds_read_b128 v[216:219], v198 offset:37888
	ds_read_b128 v[220:223], v198 offset:38912
	ds_read_b128 v[242:245], v198 offset:39936
	global_load_lds_dwordx4 v[250:251], off
	v_lshl_add_u64 v[250:251], s[10:11], 0, v[166:167]
	s_mov_b32 m0, s34
	s_nop 0
	global_load_lds_dwordx4 v[250:251], off
	s_waitcnt vmcnt(8)
	s_waitcnt lgkmcnt(0)
	s_barrier
	s_waitcnt lgkmcnt(0)
	v_mfma_f32_16x16x32_bf16 v[158:161], v[64:67], v[176:179], v[158:161]
	v_mfma_f32_16x16x32_bf16 v[154:157], v[88:91], v[176:179], v[154:157]
	v_mfma_f32_16x16x32_bf16 v[142:145], v[64:67], v[204:207], v[142:145]
	v_mfma_f32_16x16x32_bf16 v[138:141], v[88:91], v[204:207], v[138:141]
	v_mfma_f32_16x16x32_bf16 v[118:121], v[64:67], v[212:215], v[118:121]
	v_mfma_f32_16x16x32_bf16 v[114:117], v[88:91], v[212:215], v[114:117]
	v_mfma_f32_16x16x32_bf16 v[84:87], v[64:67], v[220:223], v[84:87]
	v_mfma_f32_16x16x32_bf16 v[80:83], v[88:91], v[220:223], v[80:83]
	v_mfma_f32_16x16x32_bf16 v[158:161], v[68:71], v[200:203], v[158:161]
	v_mfma_f32_16x16x32_bf16 v[154:157], v[92:95], v[200:203], v[154:157]
	v_mfma_f32_16x16x32_bf16 v[142:145], v[68:71], v[208:211], v[142:145]
	v_mfma_f32_16x16x32_bf16 v[138:141], v[92:95], v[208:211], v[138:141]
	v_mfma_f32_16x16x32_bf16 v[118:121], v[68:71], v[216:219], v[118:121]
	v_mfma_f32_16x16x32_bf16 v[114:117], v[92:95], v[216:219], v[114:117]
	v_mfma_f32_16x16x32_bf16 v[84:87], v[68:71], v[242:245], v[84:87]
	v_mfma_f32_16x16x32_bf16 v[80:83], v[92:95], v[242:245], v[80:83]
	v_mfma_f32_16x16x32_bf16 v[150:153], v[106:109], v[176:179], v[150:153]
	v_mfma_f32_16x16x32_bf16 v[146:149], v[130:133], v[176:179], v[146:149]
	v_mfma_f32_16x16x32_bf16 v[126:129], v[106:109], v[204:207], v[126:129]
	v_mfma_f32_16x16x32_bf16 v[122:125], v[130:133], v[204:207], v[122:125]
	v_mfma_f32_16x16x32_bf16 v[102:105], v[106:109], v[212:215], v[102:105]
	v_mfma_f32_16x16x32_bf16 v[98:101], v[130:133], v[212:215], v[98:101]
	v_mfma_f32_16x16x32_bf16 v[76:79], v[106:109], v[220:223], v[76:79]
	v_mfma_f32_16x16x32_bf16 v[72:75], v[130:133], v[220:223], v[72:75]
	v_mfma_f32_16x16x32_bf16 v[150:153], v[110:113], v[200:203], v[150:153]
	v_mfma_f32_16x16x32_bf16 v[146:149], v[134:137], v[200:203], v[146:149]
	v_mfma_f32_16x16x32_bf16 v[126:129], v[110:113], v[208:211], v[126:129]
	v_mfma_f32_16x16x32_bf16 v[122:125], v[134:137], v[208:211], v[122:125]
	v_mfma_f32_16x16x32_bf16 v[102:105], v[110:113], v[216:219], v[102:105]
	v_mfma_f32_16x16x32_bf16 v[98:101], v[134:137], v[216:219], v[98:101]
	v_mfma_f32_16x16x32_bf16 v[76:79], v[110:113], v[242:245], v[76:79]
	v_mfma_f32_16x16x32_bf16 v[72:75], v[134:137], v[242:245], v[72:75]
	s_barrier
; #define PG8_STAGE(bufoff, gbase, voff) do { _Pragma("unroll") for (int _i = 0; _i < 2; ++_i) \
;         __builtin_amdgcn_global_load_lds((const unsigned*)((const char*)(gbase) + (voff)[_i]), (PG8_LAS unsigned*)(lds + (bufoff) + ldsw + _i * 8192), 16, 0, 0); } while (0)
; #define PG8_LDA(dst, b, h) do { _Pragma("unroll") for (int m = 0; m < 4; ++m) _Pragma("unroll") for (int k = 0; k < 2; ++k) dst[m][k] = *(const PG8_LAS bf16x8*)(lds + PG8_SA(b, h) + aoff + m * 2048 + k * 1024); } while (0)
; #define PG8_MMA(ai, bj, At, Bt) do { __builtin_amdgcn_s_setprio(1); _Pragma("unroll") for (int m = 0; m < 4; ++m) _Pragma("unroll") for (int n = 0; n < 2; ++n) _Pragma("unroll") for (int k = 0; k < 2; ++k) \
;         acc[ai][bj][m][n] = __builtin_amdgcn_mfma_f32_16x16x32_bf16(Bt[n][k], At[m][k], acc[ai][bj][m][n], 0, 0, 0); __builtin_amdgcn_s_setprio(0); } while (0)
; #define PG8_WAIT_V(n) asm volatile("s_waitcnt vmcnt(" #n ")" ::: "memory")
; #define PG8_WAIT_L(n) asm volatile("s_waitcnt lgkmcnt(" #n ")" ::: "memory")
; #define PG8_BAR __builtin_amdgcn_s_barrier()
; #define PG8_SCHED __builtin_amdgcn_sched_barrier(0)
; template <class Epi, class Sched, bool ALIGN_EPI = false, bool SP2 = false>
; __device__ __forceinline__ void gemm_phase(PG8_LAS unsigned char* lds, const Gemm g, const Sched& S, const Epi& E, const int tid_in) {
;     ...
;             PG8_LDA(At, 1, 1); PG8_STAGE(PG8_SB(1, 0), b3, voffB); PG8_STAGE(PG8_SB(1, 1), b3 + hstep, voffB); PG8_STAGE(PG8_SA(1, 0), a3, voffA);
;             PG8_WAIT_V(8); PG8_WAIT_L(0); PG8_BAR; PG8_MMA(1, 0, At, B0); PG8_MMA(1, 1, At, B1); PG8_BAR; PG8_SCHED;
;     ...
;         if constexpr (ALIGN_EPI) { if (wr == 0) PG8_BAR; }
	s_add_i32 s10, s61, s19
	v_lshl_add_u64 v[180:181], v[180:181], 0, s[2:3]
	s_mov_b32 m0, s10
	ds_read_b128 v[176:179], v198 offset:49152
	ds_read_b128 v[200:203], v198 offset:50176
	ds_read_b128 v[204:207], v198 offset:51200
	ds_read_b128 v[208:211], v198 offset:52224
	ds_read_b128 v[212:215], v198 offset:53248
	ds_read_b128 v[216:219], v198 offset:54272
	ds_read_b128 v[220:223], v198 offset:55296
	ds_read_b128 v[242:245], v198 offset:56320
	global_load_lds_dwordx4 v[180:181], off
	s_add_i32 m0, s10, 0x2000
	s_add_u32 s8, s8, 0x80080
	v_lshl_add_u64 v[180:181], v[184:185], 0, s[2:3]
	s_addc_u32 s9, s9, 0
	s_add_i32 s10, s62, s19
	global_load_lds_dwordx4 v[180:181], off
	v_lshl_add_u64 v[180:181], s[8:9], 0, v[164:165]
	s_mov_b32 m0, s10
	s_nop 0
	global_load_lds_dwordx4 v[180:181], off
	v_lshl_add_u64 v[180:181], s[8:9], 0, v[168:169]
	s_add_i32 m0, s10, 0x2000
	s_nop 0
	global_load_lds_dwordx4 v[180:181], off
	v_lshl_add_u64 v[180:181], v[186:187], 0, s[2:3]
	s_mov_b32 m0, s46
	s_nop 0
	global_load_lds_dwordx4 v[180:181], off
	v_lshl_add_u64 v[180:181], v[224:225], 0, s[2:3]
	s_mov_b32 m0, s49
	s_nop 0
	global_load_lds_dwordx4 v[180:181], off
	s_waitcnt vmcnt(8)
	s_waitcnt lgkmcnt(0)
	s_barrier
	s_waitcnt lgkmcnt(0)
	v_mfma_f32_16x16x32_bf16 v[60:63], v[64:67], v[176:179], v[60:63]
	v_mfma_f32_16x16x32_bf16 v[56:59], v[88:91], v[176:179], v[56:59]
	v_mfma_f32_16x16x32_bf16 v[44:47], v[64:67], v[204:207], v[44:47]
	v_mfma_f32_16x16x32_bf16 v[40:43], v[88:91], v[204:207], v[40:43]
	v_mfma_f32_16x16x32_bf16 v[28:31], v[64:67], v[212:215], v[28:31]
	v_mfma_f32_16x16x32_bf16 v[24:27], v[88:91], v[212:215], v[24:27]
	v_mfma_f32_16x16x32_bf16 v[12:15], v[64:67], v[220:223], v[12:15]
	v_mfma_f32_16x16x32_bf16 v[8:11], v[88:91], v[220:223], v[8:11]
	v_mfma_f32_16x16x32_bf16 v[60:63], v[68:71], v[200:203], v[60:63]
	v_mfma_f32_16x16x32_bf16 v[56:59], v[92:95], v[200:203], v[56:59]
	v_mfma_f32_16x16x32_bf16 v[44:47], v[68:71], v[208:211], v[44:47]
	v_mfma_f32_16x16x32_bf16 v[40:43], v[92:95], v[208:211], v[40:43]
	v_mfma_f32_16x16x32_bf16 v[28:31], v[68:71], v[216:219], v[28:31]
	v_mfma_f32_16x16x32_bf16 v[24:27], v[92:95], v[216:219], v[24:27]
	v_mfma_f32_16x16x32_bf16 v[12:15], v[68:71], v[242:245], v[12:15]
	v_mfma_f32_16x16x32_bf16 v[8:11], v[92:95], v[242:245], v[8:11]
	v_mfma_f32_16x16x32_bf16 v[52:55], v[106:109], v[176:179], v[52:55]
	v_mfma_f32_16x16x32_bf16 v[48:51], v[130:133], v[176:179], v[48:51]
	v_mfma_f32_16x16x32_bf16 v[36:39], v[106:109], v[204:207], v[36:39]
	v_mfma_f32_16x16x32_bf16 v[32:35], v[130:133], v[204:207], v[32:35]
	v_mfma_f32_16x16x32_bf16 v[20:23], v[106:109], v[212:215], v[20:23]
	v_mfma_f32_16x16x32_bf16 v[16:19], v[130:133], v[212:215], v[16:19]
	v_mfma_f32_16x16x32_bf16 v[4:7], v[106:109], v[220:223], v[4:7]
	v_mfma_f32_16x16x32_bf16 v[0:3], v[130:133], v[220:223], v[0:3]
	v_mfma_f32_16x16x32_bf16 v[52:55], v[110:113], v[200:203], v[52:55]
	v_mfma_f32_16x16x32_bf16 v[48:51], v[134:137], v[200:203], v[48:51]
	v_mfma_f32_16x16x32_bf16 v[36:39], v[110:113], v[208:211], v[36:39]
	v_mfma_f32_16x16x32_bf16 v[32:35], v[134:137], v[208:211], v[32:35]
	v_mfma_f32_16x16x32_bf16 v[20:23], v[110:113], v[216:219], v[20:23]
	v_mfma_f32_16x16x32_bf16 v[16:19], v[134:137], v[216:219], v[16:19]
	v_mfma_f32_16x16x32_bf16 v[4:7], v[110:113], v[242:245], v[4:7]
	v_mfma_f32_16x16x32_bf16 v[0:3], v[134:137], v[242:245], v[0:3]
	s_barrier
	s_add_i32 s57, s57, 2
	s_add_u32 s42, s42, 0x100
	s_addc_u32 s43, s43, 0
	s_add_u32 s45, s45, 0x100
	s_addc_u32 s55, s55, 0
	s_cmp_gt_u32 s57, 29
	s_cbranch_scc0 .LBB0_593
	s_setprio 0
	s_and_b64 vcc, exec, s[50:51]
	s_cbranch_vccz .LBB0_596
	s_barrier
